# weight transpose items: the 8 loads of each loop trip get their own registers and one wait (4 memory round trips per item instead of 32)
# speedup vs baseline: 1.0486x; 1.0195x over previous
; #define LAS __attribute__((address_space(3)))
; DEV void tr_item(const float* W, int ldw, int K, bf16_t* WT, int dst_n0, int src_n0, int k0, LAS float* scr, int lane) {
; #pragma unroll 8
;     for (int i = 0; i < 32; ++i) { const int kk = 2 * i + (lane >> 5); scr[kk * 33 + (lane & 31)] = (src_n0 >= 0) ? W[(size_t)(k0 + kk) * ldw + src_n0 + (lane & 31)] : 0.f; }
;     asm volatile("s_waitcnt lgkmcnt(0)" ::: "memory");
.LBB0_24:
	s_add_i32 s4, s4, 16
	s_waitcnt vmcnt(0)
	ds_write_b32 v19, v104
	ds_write_b32 v19, v105 offset:264
	ds_write_b32 v19, v106 offset:528
	ds_write_b32 v19, v107 offset:792
	ds_write_b32 v19, v108 offset:1056
	ds_write_b32 v19, v109 offset:1320
	ds_write_b32 v19, v110 offset:1584
	ds_write_b32 v19, v111 offset:1848
	s_cmp_lg_u32 s4, 64
	v_add_u32_e32 v19, 0x840, v19
	s_cbranch_scc0 .LBB0_22
.LBB0_25:
	v_mov_b32_e32 v104, 0
	v_mov_b32_e32 v105, 0
	v_mov_b32_e32 v106, 0
	v_mov_b32_e32 v107, 0
	v_mov_b32_e32 v108, 0
	v_mov_b32_e32 v109, 0
	v_mov_b32_e32 v110, 0
	v_mov_b32_e32 v111, 0
	v_mov_b32_e32 v20, 0
	s_and_b64 vcc, exec, s[2:3]
	v_mov_b32_e32 v21, 0
	s_cbranch_vccnz .LBB0_27
	v_add_u32_e32 v22, s4, v18
	v_ashrrev_i32_e32 v23, 31, v22
	v_lshlrev_b64 v[22:23], 13, v[22:23]
	v_lshl_add_u64 v[22:23], v[16:17], 0, v[22:23]
	global_load_dword v104, v[22:23], off
.LBB0_27:
	s_and_b64 vcc, exec, s[2:3]
	s_cbranch_vccnz .LBB0_29
	v_add3_u32 v20, v18, s4, 2
	v_ashrrev_i32_e32 v21, 31, v20
	v_lshlrev_b64 v[20:21], 13, v[20:21]
	v_lshl_add_u64 v[20:21], v[16:17], 0, v[20:21]
	global_load_dword v105, v[20:21], off
.LBB0_29:
	v_mov_b32_e32 v20, 0
	s_and_b64 vcc, exec, s[2:3]
	v_mov_b32_e32 v21, 0
	s_cbranch_vccnz .LBB0_31
	v_add3_u32 v22, v18, s4, 4
	v_ashrrev_i32_e32 v23, 31, v22
	v_lshlrev_b64 v[22:23], 13, v[22:23]
	v_lshl_add_u64 v[22:23], v[16:17], 0, v[22:23]
	global_load_dword v106, v[22:23], off
.LBB0_31:
	s_and_b64 vcc, exec, s[2:3]
	s_cbranch_vccnz .LBB0_33
	v_add3_u32 v20, v18, s4, 6
	v_ashrrev_i32_e32 v21, 31, v20
	v_lshlrev_b64 v[20:21], 13, v[20:21]
	v_lshl_add_u64 v[20:21], v[16:17], 0, v[20:21]
	global_load_dword v107, v[20:21], off
.LBB0_33:
	v_mov_b32_e32 v20, 0
	s_and_b64 vcc, exec, s[2:3]
	v_mov_b32_e32 v21, 0
	s_cbranch_vccnz .LBB0_35
	v_add3_u32 v22, v18, s4, 8
	v_ashrrev_i32_e32 v23, 31, v22
	v_lshlrev_b64 v[22:23], 13, v[22:23]
	v_lshl_add_u64 v[22:23], v[16:17], 0, v[22:23]
	global_load_dword v108, v[22:23], off
.LBB0_35:
	s_and_b64 vcc, exec, s[2:3]
	s_cbranch_vccnz .LBB0_37
	v_add3_u32 v20, v18, s4, 10
	v_ashrrev_i32_e32 v21, 31, v20
	v_lshlrev_b64 v[20:21], 13, v[20:21]
	v_lshl_add_u64 v[20:21], v[16:17], 0, v[20:21]
	global_load_dword v109, v[20:21], off
.LBB0_37:
	v_mov_b32_e32 v20, 0
	s_and_b64 vcc, exec, s[2:3]
	v_mov_b32_e32 v21, 0
	s_cbranch_vccnz .LBB0_39
	v_add3_u32 v22, v18, s4, 12
	v_ashrrev_i32_e32 v23, 31, v22
	v_lshlrev_b64 v[22:23], 13, v[22:23]
	v_lshl_add_u64 v[22:23], v[16:17], 0, v[22:23]
	global_load_dword v110, v[22:23], off
.LBB0_39:
	s_and_b64 vcc, exec, s[2:3]
	s_cbranch_vccnz .LBB0_24
	v_add3_u32 v20, v18, s4, 14
	v_ashrrev_i32_e32 v21, 31, v20
	v_lshlrev_b64 v[20:21], 13, v[20:21]
	v_lshl_add_u64 v[20:21], v[16:17], 0, v[20:21]
	global_load_dword v111, v[20:21], off
	s_branch .LBB0_24

; #define LAS __attribute__((address_space(3)))
; DEV void tr_item(const float* W, int ldw, int K, bf16_t* WT, int dst_n0, int src_n0, int k0, LAS float* scr, int lane) {
; #pragma unroll 8
;     for (int i = 0; i < 32; ++i) { const int kk = 2 * i + (lane >> 5); scr[kk * 33 + (lane & 31)] = (src_n0 >= 0) ? W[(size_t)(k0 + kk) * ldw + src_n0 + (lane & 31)] : 0.f; }
;     asm volatile("s_waitcnt lgkmcnt(0)" ::: "memory");
.LBB0_46:
	v_mov_b32_e32 v104, 0
	v_mov_b32_e32 v105, 0
	v_mov_b32_e32 v106, 0
	v_mov_b32_e32 v107, 0
	v_mov_b32_e32 v108, 0
	v_mov_b32_e32 v109, 0
	v_mov_b32_e32 v110, 0
	v_mov_b32_e32 v111, 0
	v_cndmask_b32_e64 v21, 0, 1, s[8:9]
	v_mov_b32_e32 v20, 0
	v_cmp_ne_u32_e64 s[2:3], 1, v21
	s_andn2_b64 vcc, exec, s[8:9]
	v_mov_b32_e32 v21, 0
	s_cbranch_vccnz .LBB0_48
	v_add_u32_e32 v22, s4, v18
	v_ashrrev_i32_e32 v23, 31, v22
	v_lshlrev_b64 v[22:23], 12, v[22:23]
	v_lshl_add_u64 v[22:23], v[16:17], 0, v[22:23]
	global_load_dword v104, v[22:23], off
.LBB0_48:
	s_and_b64 vcc, exec, s[2:3]
	s_cbranch_vccnz .LBB0_50
	v_add3_u32 v20, v18, s4, 2
	v_ashrrev_i32_e32 v21, 31, v20
	v_lshlrev_b64 v[20:21], 12, v[20:21]
	v_lshl_add_u64 v[20:21], v[16:17], 0, v[20:21]
	global_load_dword v105, v[20:21], off
.LBB0_50:
	v_mov_b32_e32 v20, 0
	s_and_b64 vcc, exec, s[2:3]
	v_mov_b32_e32 v21, 0
	s_cbranch_vccnz .LBB0_52
	v_add3_u32 v22, v18, s4, 4
	v_ashrrev_i32_e32 v23, 31, v22
	v_lshlrev_b64 v[22:23], 12, v[22:23]
	v_lshl_add_u64 v[22:23], v[16:17], 0, v[22:23]
	global_load_dword v106, v[22:23], off
.LBB0_52:
	s_and_b64 vcc, exec, s[2:3]
	s_cbranch_vccnz .LBB0_54
	v_add3_u32 v20, v18, s4, 6
	v_ashrrev_i32_e32 v21, 31, v20
	v_lshlrev_b64 v[20:21], 12, v[20:21]
	v_lshl_add_u64 v[20:21], v[16:17], 0, v[20:21]
	global_load_dword v107, v[20:21], off
.LBB0_54:
	v_mov_b32_e32 v20, 0
	s_and_b64 vcc, exec, s[2:3]
	v_mov_b32_e32 v21, 0
	s_cbranch_vccnz .LBB0_56
	v_add3_u32 v22, v18, s4, 8
	v_ashrrev_i32_e32 v23, 31, v22
	v_lshlrev_b64 v[22:23], 12, v[22:23]
	v_lshl_add_u64 v[22:23], v[16:17], 0, v[22:23]
	global_load_dword v108, v[22:23], off
.LBB0_56:
	s_and_b64 vcc, exec, s[2:3]
	s_cbranch_vccnz .LBB0_58
	v_add3_u32 v20, v18, s4, 10
	v_ashrrev_i32_e32 v21, 31, v20
	v_lshlrev_b64 v[20:21], 12, v[20:21]
	v_lshl_add_u64 v[20:21], v[16:17], 0, v[20:21]
	global_load_dword v109, v[20:21], off
.LBB0_58:
	v_mov_b32_e32 v20, 0
	s_and_b64 vcc, exec, s[2:3]
	v_mov_b32_e32 v21, 0
	s_cbranch_vccnz .LBB0_60
	v_add3_u32 v22, v18, s4, 12
	v_ashrrev_i32_e32 v23, 31, v22
	v_lshlrev_b64 v[22:23], 12, v[22:23]
	v_lshl_add_u64 v[22:23], v[16:17], 0, v[22:23]
	global_load_dword v110, v[22:23], off
.LBB0_60:
	s_and_b64 vcc, exec, s[2:3]
	s_cbranch_vccnz .LBB0_45
	v_add3_u32 v20, v18, s4, 14
	v_ashrrev_i32_e32 v21, 31, v20
	v_lshlrev_b64 v[20:21], 12, v[20:21]
	v_lshl_add_u64 v[20:21], v[16:17], 0, v[20:21]
	global_load_dword v111, v[20:21], off
	s_branch .LBB0_45

; #define LAS __attribute__((address_space(3)))
; DEV void tr_item(const float* W, int ldw, int K, bf16_t* WT, int dst_n0, int src_n0, int k0, LAS float* scr, int lane) {
; #pragma unroll 8
;     for (int i = 0; i < 32; ++i) { const int kk = 2 * i + (lane >> 5); scr[kk * 33 + (lane & 31)] = (src_n0 >= 0) ? W[(size_t)(k0 + kk) * ldw + src_n0 + (lane & 31)] : 0.f; }
;     asm volatile("s_waitcnt lgkmcnt(0)" ::: "memory");
.LBB0_66:
	s_add_u32 s10, s10, 0x58000
	s_addc_u32 s11, s11, 0
	s_waitcnt vmcnt(0)
	ds_write_b32 v46, v104
	ds_write_b32 v46, v105 offset:264
	ds_write_b32 v46, v106 offset:528
	ds_write_b32 v46, v107 offset:792
	ds_write_b32 v46, v108 offset:1056
	ds_write_b32 v46, v109 offset:1320
	ds_write_b32 v46, v110 offset:1584
	ds_write_b32 v46, v111 offset:1848
	s_cmp_lg_u32 s10, 0x160000
	v_add_u32_e32 v46, 0x840, v46
	s_cbranch_scc0 .LBB0_64
.LBB0_67:
	v_mov_b32_e32 v104, 0
	v_mov_b32_e32 v105, 0
	v_mov_b32_e32 v106, 0
	v_mov_b32_e32 v107, 0
	v_mov_b32_e32 v108, 0
	v_mov_b32_e32 v109, 0
	v_mov_b32_e32 v110, 0
	v_mov_b32_e32 v111, 0
	v_cndmask_b32_e64 v48, 0, 1, s[8:9]
	v_mov_b32_e32 v47, 0
	v_cmp_ne_u32_e64 s[2:3], 1, v48
	s_andn2_b64 vcc, exec, s[8:9]
	v_mov_b32_e32 v48, 0
	s_cbranch_vccnz .LBB0_69
	v_lshl_add_u64 v[48:49], v[30:31], 0, s[10:11]
	global_load_dword v104, v[48:49], off
.LBB0_69:
	s_and_b64 vcc, exec, s[2:3]
	s_cbranch_vccnz .LBB0_71
	v_lshl_add_u64 v[48:49], v[28:29], 0, s[10:11]
	global_load_dword v105, v[48:49], off
.LBB0_71:
	v_mov_b32_e32 v47, 0
	s_and_b64 vcc, exec, s[2:3]
	v_mov_b32_e32 v48, 0
	s_cbranch_vccnz .LBB0_73
	v_lshl_add_u64 v[48:49], v[26:27], 0, s[10:11]
	global_load_dword v106, v[48:49], off
.LBB0_73:
	s_and_b64 vcc, exec, s[2:3]
	s_cbranch_vccnz .LBB0_75
	v_lshl_add_u64 v[48:49], v[24:25], 0, s[10:11]
	global_load_dword v107, v[48:49], off
.LBB0_75:
	v_mov_b32_e32 v47, 0
	s_and_b64 vcc, exec, s[2:3]
	v_mov_b32_e32 v48, 0
	s_cbranch_vccnz .LBB0_77
	v_lshl_add_u64 v[48:49], v[22:23], 0, s[10:11]
	global_load_dword v108, v[48:49], off
.LBB0_77:
	s_and_b64 vcc, exec, s[2:3]
	s_cbranch_vccnz .LBB0_79
	v_lshl_add_u64 v[48:49], v[20:21], 0, s[10:11]
	global_load_dword v109, v[48:49], off
.LBB0_79:
	v_mov_b32_e32 v47, 0
	s_and_b64 vcc, exec, s[2:3]
	v_mov_b32_e32 v48, 0
	s_cbranch_vccnz .LBB0_81
	v_lshl_add_u64 v[48:49], v[18:19], 0, s[10:11]
	global_load_dword v110, v[48:49], off
.LBB0_81:
	s_and_b64 vcc, exec, s[2:3]
	s_cbranch_vccnz .LBB0_66
	v_lshl_add_u64 v[48:49], v[16:17], 0, s[10:11]
	global_load_dword v111, v[48:49], off
	s_branch .LBB0_66

; #define LAS __attribute__((address_space(3)))
; DEV void tr_item(const float* W, int ldw, int K, bf16_t* WT, int dst_n0, int src_n0, int k0, LAS float* scr, int lane) {
; #pragma unroll 8
;     for (int i = 0; i < 32; ++i) { const int kk = 2 * i + (lane >> 5); scr[kk * 33 + (lane & 31)] = (src_n0 >= 0) ? W[(size_t)(k0 + kk) * ldw + src_n0 + (lane & 31)] : 0.f; }
;     asm volatile("s_waitcnt lgkmcnt(0)" ::: "memory");
.LBB0_681:
	s_add_i32 s5, s5, 16
	s_waitcnt vmcnt(0)
	ds_write_b32 v15, v104
	ds_write_b32 v15, v105 offset:264
	ds_write_b32 v15, v106 offset:528
	ds_write_b32 v15, v107 offset:792
	ds_write_b32 v15, v108 offset:1056
	ds_write_b32 v15, v109 offset:1320
	ds_write_b32 v15, v110 offset:1584
	ds_write_b32 v15, v111 offset:1848
	s_cmp_lg_u32 s5, 64
	v_add_u32_e32 v15, 0x840, v15
	s_cbranch_scc0 .LBB0_679
.LBB0_682:
	v_mov_b32_e32 v104, 0
	v_mov_b32_e32 v105, 0
	v_mov_b32_e32 v106, 0
	v_mov_b32_e32 v107, 0
	v_mov_b32_e32 v108, 0
	v_mov_b32_e32 v109, 0
	v_mov_b32_e32 v110, 0
	v_mov_b32_e32 v111, 0
	v_cndmask_b32_e64 v17, 0, 1, s[8:9]
	v_mov_b32_e32 v16, 0
	v_cmp_ne_u32_e64 s[2:3], 1, v17
	s_andn2_b64 vcc, exec, s[8:9]
	v_mov_b32_e32 v17, 0
	s_cbranch_vccnz .LBB0_684
	v_add_u32_e32 v17, s5, v14
	v_mad_i64_i32 v[18:19], s[14:15], v17, s33, v[6:7]
	global_load_dword v104, v[18:19], off
.LBB0_684:
	s_and_b64 vcc, exec, s[2:3]
	s_cbranch_vccnz .LBB0_686
	v_add3_u32 v16, v14, s5, 2
	v_mad_i64_i32 v[16:17], s[14:15], v16, s33, v[6:7]
	global_load_dword v105, v[16:17], off
.LBB0_686:
	v_mov_b32_e32 v16, 0
	s_and_b64 vcc, exec, s[2:3]
	v_mov_b32_e32 v17, 0
	s_cbranch_vccnz .LBB0_688
	v_add3_u32 v17, v14, s5, 4
	v_mad_i64_i32 v[18:19], s[14:15], v17, s33, v[6:7]
	global_load_dword v106, v[18:19], off
.LBB0_688:
	s_and_b64 vcc, exec, s[2:3]
	s_cbranch_vccnz .LBB0_690
	v_add3_u32 v16, v14, s5, 6
	v_mad_i64_i32 v[16:17], s[14:15], v16, s33, v[6:7]
	global_load_dword v107, v[16:17], off
.LBB0_690:
	v_mov_b32_e32 v16, 0
	s_and_b64 vcc, exec, s[2:3]
	v_mov_b32_e32 v17, 0
	s_cbranch_vccnz .LBB0_692
	v_add3_u32 v17, v14, s5, 8
	v_mad_i64_i32 v[18:19], s[14:15], v17, s33, v[6:7]
	global_load_dword v108, v[18:19], off
.LBB0_692:
	s_and_b64 vcc, exec, s[2:3]
	s_cbranch_vccnz .LBB0_694
	v_add3_u32 v16, v14, s5, 10
	v_mad_i64_i32 v[16:17], s[14:15], v16, s33, v[6:7]
	global_load_dword v109, v[16:17], off
.LBB0_694:
	v_mov_b32_e32 v16, 0
	s_and_b64 vcc, exec, s[2:3]
	v_mov_b32_e32 v17, 0
	s_cbranch_vccnz .LBB0_696
	v_add3_u32 v17, v14, s5, 12
	v_mad_i64_i32 v[18:19], s[14:15], v17, s33, v[6:7]
	global_load_dword v110, v[18:19], off
.LBB0_696:
	s_and_b64 vcc, exec, s[2:3]
	s_cbranch_vccnz .LBB0_681
	v_add3_u32 v16, v14, s5, 14
	v_mad_i64_i32 v[16:17], s[2:3], v16, s33, v[6:7]
	global_load_dword v111, v[16:17], off
	s_branch .LBB0_681

; #define LAS __attribute__((address_space(3)))
; DEV void tr_item(const float* W, int ldw, int K, bf16_t* WT, int dst_n0, int src_n0, int k0, LAS float* scr, int lane) {
; #pragma unroll 8
;     for (int i = 0; i < 32; ++i) { const int kk = 2 * i + (lane >> 5); scr[kk * 33 + (lane & 31)] = (src_n0 >= 0) ? W[(size_t)(k0 + kk) * ldw + src_n0 + (lane & 31)] : 0.f; }
;     asm volatile("s_waitcnt lgkmcnt(0)" ::: "memory");
.LBB0_705:
	v_mov_b32_e32 v104, 0
	v_mov_b32_e32 v105, 0
	v_mov_b32_e32 v106, 0
	v_mov_b32_e32 v107, 0
	v_mov_b32_e32 v108, 0
	v_mov_b32_e32 v109, 0
	v_mov_b32_e32 v110, 0
	v_mov_b32_e32 v111, 0
	v_cndmask_b32_e64 v17, 0, 1, s[8:9]
	v_mov_b32_e32 v16, 0
	v_cmp_ne_u32_e64 s[2:3], 1, v17
	s_andn2_b64 vcc, exec, s[8:9]
	v_mov_b32_e32 v17, 0
	s_cbranch_vccnz .LBB0_707
	v_add_u32_e32 v17, s5, v14
	s_movk_i32 s14, 0x1800
	v_mad_i64_i32 v[18:19], s[14:15], v17, s14, v[6:7]
	global_load_dword v104, v[18:19], off
.LBB0_707:
	s_and_b64 vcc, exec, s[2:3]
	s_cbranch_vccnz .LBB0_709
	v_add3_u32 v16, v14, s5, 2
	s_movk_i32 s14, 0x1800
	v_mad_i64_i32 v[16:17], s[14:15], v16, s14, v[6:7]
	global_load_dword v105, v[16:17], off
.LBB0_709:
	v_mov_b32_e32 v16, 0
	s_and_b64 vcc, exec, s[2:3]
	v_mov_b32_e32 v17, 0
	s_cbranch_vccnz .LBB0_711
	v_add3_u32 v17, v14, s5, 4
	s_movk_i32 s14, 0x1800
	v_mad_i64_i32 v[18:19], s[14:15], v17, s14, v[6:7]
	global_load_dword v106, v[18:19], off
.LBB0_711:
	s_and_b64 vcc, exec, s[2:3]
	s_cbranch_vccnz .LBB0_713
	v_add3_u32 v16, v14, s5, 6
	s_movk_i32 s14, 0x1800
	v_mad_i64_i32 v[16:17], s[14:15], v16, s14, v[6:7]
	global_load_dword v107, v[16:17], off
.LBB0_713:
	v_mov_b32_e32 v16, 0
	s_and_b64 vcc, exec, s[2:3]
	v_mov_b32_e32 v17, 0
	s_cbranch_vccnz .LBB0_715
	v_add3_u32 v17, v14, s5, 8
	s_movk_i32 s14, 0x1800
	v_mad_i64_i32 v[18:19], s[14:15], v17, s14, v[6:7]
	global_load_dword v108, v[18:19], off
.LBB0_715:
	s_and_b64 vcc, exec, s[2:3]
	s_cbranch_vccnz .LBB0_717
	v_add3_u32 v16, v14, s5, 10
	s_movk_i32 s14, 0x1800
	v_mad_i64_i32 v[16:17], s[14:15], v16, s14, v[6:7]
	global_load_dword v109, v[16:17], off
.LBB0_717:
	v_mov_b32_e32 v16, 0
	s_and_b64 vcc, exec, s[2:3]
	v_mov_b32_e32 v17, 0
	s_cbranch_vccnz .LBB0_719
	v_add3_u32 v17, v14, s5, 12
	s_movk_i32 s14, 0x1800
	v_mad_i64_i32 v[18:19], s[14:15], v17, s14, v[6:7]
	global_load_dword v110, v[18:19], off
.LBB0_719:
	s_and_b64 vcc, exec, s[2:3]
	s_cbranch_vccnz .LBB0_704
	v_add3_u32 v16, v14, s5, 14
	s_movk_i32 s2, 0x1800
	v_mad_i64_i32 v[16:17], s[2:3], v16, s2, v[6:7]
	global_load_dword v111, v[16:17], off
	s_branch .LBB0_704

; #define LAS __attribute__((address_space(3)))
; DEV void tr_item(const float* W, int ldw, int K, bf16_t* WT, int dst_n0, int src_n0, int k0, LAS float* scr, int lane) {
; #pragma unroll 8
;     for (int i = 0; i < 32; ++i) { const int kk = 2 * i + (lane >> 5); scr[kk * 33 + (lane & 31)] = (src_n0 >= 0) ? W[(size_t)(k0 + kk) * ldw + src_n0 + (lane & 31)] : 0.f; }
;     asm volatile("s_waitcnt lgkmcnt(0)" ::: "memory");
.LBB0_726:
	v_mov_b32_e32 v104, 0
	v_mov_b32_e32 v105, 0
	v_mov_b32_e32 v106, 0
	v_mov_b32_e32 v107, 0
	v_mov_b32_e32 v108, 0
	v_mov_b32_e32 v109, 0
	v_mov_b32_e32 v110, 0
	v_mov_b32_e32 v111, 0
	v_cndmask_b32_e64 v17, 0, 1, s[8:9]
	v_mov_b32_e32 v16, 0
	v_cmp_ne_u32_e64 s[2:3], 1, v17
	s_andn2_b64 vcc, exec, s[8:9]
	v_mov_b32_e32 v17, 0
	s_cbranch_vccnz .LBB0_728
	v_add_u32_e32 v18, s5, v14
	v_ashrrev_i32_e32 v19, 31, v18
	v_lshlrev_b64 v[18:19], 13, v[18:19]
	v_lshl_add_u64 v[18:19], v[6:7], 0, v[18:19]
	global_load_dword v104, v[18:19], off
.LBB0_728:
	s_and_b64 vcc, exec, s[2:3]
	s_cbranch_vccnz .LBB0_730
	v_add3_u32 v16, v14, s5, 2
	v_ashrrev_i32_e32 v17, 31, v16
	v_lshlrev_b64 v[16:17], 13, v[16:17]
	v_lshl_add_u64 v[16:17], v[6:7], 0, v[16:17]
	global_load_dword v105, v[16:17], off
.LBB0_730:
	v_mov_b32_e32 v16, 0
	s_and_b64 vcc, exec, s[2:3]
	v_mov_b32_e32 v17, 0
	s_cbranch_vccnz .LBB0_732
	v_add3_u32 v18, v14, s5, 4
	v_ashrrev_i32_e32 v19, 31, v18
	v_lshlrev_b64 v[18:19], 13, v[18:19]
	v_lshl_add_u64 v[18:19], v[6:7], 0, v[18:19]
	global_load_dword v106, v[18:19], off
.LBB0_732:
	s_and_b64 vcc, exec, s[2:3]
	s_cbranch_vccnz .LBB0_734
	v_add3_u32 v16, v14, s5, 6
	v_ashrrev_i32_e32 v17, 31, v16
	v_lshlrev_b64 v[16:17], 13, v[16:17]
	v_lshl_add_u64 v[16:17], v[6:7], 0, v[16:17]
	global_load_dword v107, v[16:17], off
.LBB0_734:
	v_mov_b32_e32 v16, 0
	s_and_b64 vcc, exec, s[2:3]
	v_mov_b32_e32 v17, 0
	s_cbranch_vccnz .LBB0_736
	v_add3_u32 v18, v14, s5, 8
	v_ashrrev_i32_e32 v19, 31, v18
	v_lshlrev_b64 v[18:19], 13, v[18:19]
	v_lshl_add_u64 v[18:19], v[6:7], 0, v[18:19]
	global_load_dword v108, v[18:19], off
.LBB0_736:
	s_and_b64 vcc, exec, s[2:3]
	s_cbranch_vccnz .LBB0_738
	v_add3_u32 v16, v14, s5, 10
	v_ashrrev_i32_e32 v17, 31, v16
	v_lshlrev_b64 v[16:17], 13, v[16:17]
	v_lshl_add_u64 v[16:17], v[6:7], 0, v[16:17]
	global_load_dword v109, v[16:17], off
.LBB0_738:
	v_mov_b32_e32 v16, 0
	s_and_b64 vcc, exec, s[2:3]
	v_mov_b32_e32 v17, 0
	s_cbranch_vccnz .LBB0_740
	v_add3_u32 v18, v14, s5, 12
	v_ashrrev_i32_e32 v19, 31, v18
	v_lshlrev_b64 v[18:19], 13, v[18:19]
	v_lshl_add_u64 v[18:19], v[6:7], 0, v[18:19]
	global_load_dword v110, v[18:19], off
.LBB0_740:
	s_and_b64 vcc, exec, s[2:3]
	s_cbranch_vccnz .LBB0_725
	v_add3_u32 v16, v14, s5, 14
	v_ashrrev_i32_e32 v17, 31, v16
	v_lshlrev_b64 v[16:17], 13, v[16:17]
	v_lshl_add_u64 v[16:17], v[6:7], 0, v[16:17]
	global_load_dword v111, v[16:17], off
	s_branch .LBB0_725

; #define LAS __attribute__((address_space(3)))
; DEV void tr_item(const float* W, int ldw, int K, bf16_t* WT, int dst_n0, int src_n0, int k0, LAS float* scr, int lane) {
; #pragma unroll 8
;     for (int i = 0; i < 32; ++i) { const int kk = 2 * i + (lane >> 5); scr[kk * 33 + (lane & 31)] = (src_n0 >= 0) ? W[(size_t)(k0 + kk) * ldw + src_n0 + (lane & 31)] : 0.f; }
;     asm volatile("s_waitcnt lgkmcnt(0)" ::: "memory");
.LBB0_746:
	s_add_i32 s9, s9, 16
	s_waitcnt vmcnt(0)
	ds_write_b32 v15, v104
	ds_write_b32 v15, v105 offset:264
	ds_write_b32 v15, v106 offset:528
	ds_write_b32 v15, v107 offset:792
	ds_write_b32 v15, v108 offset:1056
	ds_write_b32 v15, v109 offset:1320
	ds_write_b32 v15, v110 offset:1584
	ds_write_b32 v15, v111 offset:1848
	s_cmp_lg_u32 s9, 64
	v_add_u32_e32 v15, 0x840, v15
	s_cbranch_scc0 .LBB0_744
.LBB0_747:
	v_mov_b32_e32 v104, 0
	v_mov_b32_e32 v105, 0
	v_mov_b32_e32 v106, 0
	v_mov_b32_e32 v107, 0
	v_mov_b32_e32 v108, 0
	v_mov_b32_e32 v109, 0
	v_mov_b32_e32 v110, 0
	v_mov_b32_e32 v111, 0
	v_cndmask_b32_e64 v17, 0, 1, s[4:5]
	v_mov_b32_e32 v16, 0
	v_cmp_ne_u32_e64 s[2:3], 1, v17
	s_andn2_b64 vcc, exec, s[4:5]
	v_mov_b32_e32 v17, 0
	s_cbranch_vccnz .LBB0_749
	v_add_u32_e32 v18, s9, v14
	v_ashrrev_i32_e32 v19, 31, v18
	v_lshlrev_b64 v[18:19], 12, v[18:19]
	v_lshl_add_u64 v[18:19], v[6:7], 0, v[18:19]
	global_load_dword v104, v[18:19], off
.LBB0_749:
	s_and_b64 vcc, exec, s[2:3]
	s_cbranch_vccnz .LBB0_751
	v_add3_u32 v16, v14, s9, 2
	v_ashrrev_i32_e32 v17, 31, v16
	v_lshlrev_b64 v[16:17], 12, v[16:17]
	v_lshl_add_u64 v[16:17], v[6:7], 0, v[16:17]
	global_load_dword v105, v[16:17], off
.LBB0_751:
	v_mov_b32_e32 v16, 0
	s_and_b64 vcc, exec, s[2:3]
	v_mov_b32_e32 v17, 0
	s_cbranch_vccnz .LBB0_753
	v_add3_u32 v18, v14, s9, 4
	v_ashrrev_i32_e32 v19, 31, v18
	v_lshlrev_b64 v[18:19], 12, v[18:19]
	v_lshl_add_u64 v[18:19], v[6:7], 0, v[18:19]
	global_load_dword v106, v[18:19], off
.LBB0_753:
	s_and_b64 vcc, exec, s[2:3]
	s_cbranch_vccnz .LBB0_755
	v_add3_u32 v16, v14, s9, 6
	v_ashrrev_i32_e32 v17, 31, v16
	v_lshlrev_b64 v[16:17], 12, v[16:17]
	v_lshl_add_u64 v[16:17], v[6:7], 0, v[16:17]
	global_load_dword v107, v[16:17], off
.LBB0_755:
	v_mov_b32_e32 v16, 0
	s_and_b64 vcc, exec, s[2:3]
	v_mov_b32_e32 v17, 0
	s_cbranch_vccnz .LBB0_757
	v_add3_u32 v18, v14, s9, 8
	v_ashrrev_i32_e32 v19, 31, v18
	v_lshlrev_b64 v[18:19], 12, v[18:19]
	v_lshl_add_u64 v[18:19], v[6:7], 0, v[18:19]
	global_load_dword v108, v[18:19], off
.LBB0_757:
	s_and_b64 vcc, exec, s[2:3]
	s_cbranch_vccnz .LBB0_759
	v_add3_u32 v16, v14, s9, 10
	v_ashrrev_i32_e32 v17, 31, v16
	v_lshlrev_b64 v[16:17], 12, v[16:17]
	v_lshl_add_u64 v[16:17], v[6:7], 0, v[16:17]
	global_load_dword v109, v[16:17], off
.LBB0_759:
	v_mov_b32_e32 v16, 0
	s_and_b64 vcc, exec, s[2:3]
	v_mov_b32_e32 v17, 0
	s_cbranch_vccnz .LBB0_761
	v_add3_u32 v18, v14, s9, 12
	v_ashrrev_i32_e32 v19, 31, v18
	v_lshlrev_b64 v[18:19], 12, v[18:19]
	v_lshl_add_u64 v[18:19], v[6:7], 0, v[18:19]
	global_load_dword v110, v[18:19], off
.LBB0_761:
	s_and_b64 vcc, exec, s[2:3]
	s_cbranch_vccnz .LBB0_746
	v_add3_u32 v16, v14, s9, 14
	v_ashrrev_i32_e32 v17, 31, v16
	v_lshlrev_b64 v[16:17], 12, v[16:17]
	v_lshl_add_u64 v[16:17], v[6:7], 0, v[16:17]
	global_load_dword v111, v[16:17], off
	s_branch .LBB0_746

; #define LAS __attribute__((address_space(3)))
; DEV void tr_item(const float* W, int ldw, int K, bf16_t* WT, int dst_n0, int src_n0, int k0, LAS float* scr, int lane) {
; #pragma unroll 8
;     for (int i = 0; i < 32; ++i) { const int kk = 2 * i + (lane >> 5); scr[kk * 33 + (lane & 31)] = (src_n0 >= 0) ? W[(size_t)(k0 + kk) * ldw + src_n0 + (lane & 31)] : 0.f; }
;     asm volatile("s_waitcnt lgkmcnt(0)" ::: "memory");
.LBB0_1322:
	s_add_u32 s6, s6, 0x58000
	s_addc_u32 s7, s7, 0
	s_waitcnt vmcnt(0)
	ds_write_b32 v35, v104
	ds_write_b32 v35, v105 offset:264
	ds_write_b32 v35, v106 offset:528
	ds_write_b32 v35, v107 offset:792
	ds_write_b32 v35, v108 offset:1056
	ds_write_b32 v35, v109 offset:1320
	ds_write_b32 v35, v110 offset:1584
	ds_write_b32 v35, v111 offset:1848
	s_cmp_lg_u32 s6, 0x160000
	v_add_u32_e32 v35, 0x840, v35
	s_cbranch_scc0 .LBB0_1320
.LBB0_1323:
	v_mov_b32_e32 v104, 0
	v_mov_b32_e32 v105, 0
	v_mov_b32_e32 v106, 0
	v_mov_b32_e32 v107, 0
	v_mov_b32_e32 v108, 0
	v_mov_b32_e32 v109, 0
	v_mov_b32_e32 v110, 0
	v_mov_b32_e32 v111, 0
	v_cndmask_b32_e64 v37, 0, 1, s[4:5]
	v_mov_b32_e32 v36, 0
	v_cmp_ne_u32_e64 s[2:3], 1, v37
	s_andn2_b64 vcc, exec, s[4:5]
	v_mov_b32_e32 v37, 0
	s_cbranch_vccnz .LBB0_1325
	v_lshl_add_u64 v[38:39], v[20:21], 0, s[6:7]
	global_load_dword v104, v[38:39], off
.LBB0_1325:
	s_and_b64 vcc, exec, s[2:3]
	s_cbranch_vccnz .LBB0_1327
	v_lshl_add_u64 v[36:37], v[18:19], 0, s[6:7]
	global_load_dword v105, v[36:37], off
.LBB0_1327:
	v_mov_b32_e32 v36, 0
	s_and_b64 vcc, exec, s[2:3]
	v_mov_b32_e32 v37, 0
	s_cbranch_vccnz .LBB0_1329
	v_lshl_add_u64 v[38:39], v[16:17], 0, s[6:7]
	global_load_dword v106, v[38:39], off
.LBB0_1329:
	s_and_b64 vcc, exec, s[2:3]
	s_cbranch_vccnz .LBB0_1331
	v_lshl_add_u64 v[36:37], v[14:15], 0, s[6:7]
	global_load_dword v107, v[36:37], off
.LBB0_1331:
	v_mov_b32_e32 v36, 0
	s_and_b64 vcc, exec, s[2:3]
	v_mov_b32_e32 v37, 0
	s_cbranch_vccnz .LBB0_1333
	v_lshl_add_u64 v[38:39], v[12:13], 0, s[6:7]
	global_load_dword v108, v[38:39], off
.LBB0_1333:
	s_and_b64 vcc, exec, s[2:3]
	s_cbranch_vccnz .LBB0_1335
	v_lshl_add_u64 v[36:37], v[10:11], 0, s[6:7]
	global_load_dword v109, v[36:37], off
.LBB0_1335:
	v_mov_b32_e32 v36, 0
	s_and_b64 vcc, exec, s[2:3]
	v_mov_b32_e32 v37, 0
	s_cbranch_vccnz .LBB0_1337
	v_lshl_add_u64 v[38:39], v[8:9], 0, s[6:7]
	global_load_dword v110, v[38:39], off
.LBB0_1337:
	s_and_b64 vcc, exec, s[2:3]
	s_cbranch_vccnz .LBB0_1322
	v_lshl_add_u64 v[36:37], v[6:7], 0, s[6:7]
	global_load_dword v111, v[36:37], off
	s_branch .LBB0_1322

; #define LAS __attribute__((address_space(3)))
; DEV void tr_item(const float* W, int ldw, int K, bf16_t* WT, int dst_n0, int src_n0, int k0, LAS float* scr, int lane) {
; #pragma unroll 8
;     for (int i = 0; i < 32; ++i) { const int kk = 2 * i + (lane >> 5); scr[kk * 33 + (lane & 31)] = (src_n0 >= 0) ? W[(size_t)(k0 + kk) * ldw + src_n0 + (lane & 31)] : 0.f; }
;     asm volatile("s_waitcnt lgkmcnt(0)" ::: "memory");
.LBB0_2163:
	s_add_i32 s5, s5, 16
	s_waitcnt vmcnt(0)
	ds_write_b32 v14, v104
	ds_write_b32 v14, v105 offset:264
	ds_write_b32 v14, v106 offset:528
	ds_write_b32 v14, v107 offset:792
	ds_write_b32 v14, v108 offset:1056
	ds_write_b32 v14, v109 offset:1320
	ds_write_b32 v14, v110 offset:1584
	ds_write_b32 v14, v111 offset:1848
	s_cmp_lg_u32 s5, 64
	v_add_u32_e32 v14, 0x840, v14
	s_cbranch_scc0 .LBB0_2161
.LBB0_2164:
	v_mov_b32_e32 v104, 0
	v_mov_b32_e32 v105, 0
	v_mov_b32_e32 v106, 0
	v_mov_b32_e32 v107, 0
	v_mov_b32_e32 v108, 0
	v_mov_b32_e32 v109, 0
	v_mov_b32_e32 v110, 0
	v_mov_b32_e32 v111, 0
	v_cndmask_b32_e64 v16, 0, 1, s[6:7]
	v_mov_b32_e32 v15, 0
	v_cmp_ne_u32_e64 s[2:3], 1, v16
	s_andn2_b64 vcc, exec, s[6:7]
	v_mov_b32_e32 v16, 0
	s_cbranch_vccnz .LBB0_2166
	v_add_u32_e32 v16, s5, v13
	v_ashrrev_i32_e32 v17, 31, v16
	v_lshlrev_b64 v[16:17], 12, v[16:17]
	v_lshl_add_u64 v[16:17], v[4:5], 0, v[16:17]
	global_load_dword v104, v[16:17], off
.LBB0_2166:
	s_and_b64 vcc, exec, s[2:3]
	s_cbranch_vccnz .LBB0_2168
	v_add3_u32 v16, v13, s5, 2
	v_ashrrev_i32_e32 v17, 31, v16
	v_lshlrev_b64 v[16:17], 12, v[16:17]
	v_lshl_add_u64 v[16:17], v[4:5], 0, v[16:17]
	global_load_dword v105, v[16:17], off
.LBB0_2168:
	v_mov_b32_e32 v15, 0
	s_and_b64 vcc, exec, s[2:3]
	v_mov_b32_e32 v16, 0
	s_cbranch_vccnz .LBB0_2170
	v_add3_u32 v16, v13, s5, 4
	v_ashrrev_i32_e32 v17, 31, v16
	v_lshlrev_b64 v[16:17], 12, v[16:17]
	v_lshl_add_u64 v[16:17], v[4:5], 0, v[16:17]
	global_load_dword v106, v[16:17], off
.LBB0_2170:
	s_and_b64 vcc, exec, s[2:3]
	s_cbranch_vccnz .LBB0_2172
	v_add3_u32 v16, v13, s5, 6
	v_ashrrev_i32_e32 v17, 31, v16
	v_lshlrev_b64 v[16:17], 12, v[16:17]
	v_lshl_add_u64 v[16:17], v[4:5], 0, v[16:17]
	global_load_dword v107, v[16:17], off
.LBB0_2172:
	v_mov_b32_e32 v15, 0
	s_and_b64 vcc, exec, s[2:3]
	v_mov_b32_e32 v16, 0
	s_cbranch_vccnz .LBB0_2174
	v_add3_u32 v16, v13, s5, 8
	v_ashrrev_i32_e32 v17, 31, v16
	v_lshlrev_b64 v[16:17], 12, v[16:17]
	v_lshl_add_u64 v[16:17], v[4:5], 0, v[16:17]
	global_load_dword v108, v[16:17], off
.LBB0_2174:
	s_and_b64 vcc, exec, s[2:3]
	s_cbranch_vccnz .LBB0_2176
	v_add3_u32 v16, v13, s5, 10
	v_ashrrev_i32_e32 v17, 31, v16
	v_lshlrev_b64 v[16:17], 12, v[16:17]
	v_lshl_add_u64 v[16:17], v[4:5], 0, v[16:17]
	global_load_dword v109, v[16:17], off
.LBB0_2176:
	v_mov_b32_e32 v15, 0
	s_and_b64 vcc, exec, s[2:3]
	v_mov_b32_e32 v16, 0
	s_cbranch_vccnz .LBB0_2178
	v_add3_u32 v16, v13, s5, 12
	v_ashrrev_i32_e32 v17, 31, v16
	v_lshlrev_b64 v[16:17], 12, v[16:17]
	v_lshl_add_u64 v[16:17], v[4:5], 0, v[16:17]
	global_load_dword v110, v[16:17], off
.LBB0_2178:
	s_and_b64 vcc, exec, s[2:3]
	s_cbranch_vccnz .LBB0_2163
	v_add3_u32 v16, v13, s5, 14
	v_ashrrev_i32_e32 v17, 31, v16
	v_lshlrev_b64 v[16:17], 12, v[16:17]
	v_lshl_add_u64 v[16:17], v[4:5], 0, v[16:17]
	global_load_dword v111, v[16:17], off
	s_branch .LBB0_2163
